# phase 6 w_ffn_in transpose/convert: same fix (batched scale loads, multiplies at tile loop top)
# speedup vs baseline: 1.0541x; 1.0242x over previous
.LBB0_1096:
	s_mov_b32 s3, s94
	s_cmp_lt_i32 s3, 32
	s_cbranch_scc1 .LBB0_1133
	s_sub_i32 s2, s3, 32
	v_mov_b32_e32 v14, v156
	s_cmpk_gt_u32 s2, 0x57f
	s_waitcnt vmcnt(0) lgkmcnt(0)
	s_barrier
	s_cbranch_scc1 .LBB0_1133
	s_load_dwordx4 s[12:15], s[4:5], 0xb8
	s_bfe_i32 s5, s2, 0x10005
	s_lshl_b32 s10, s2, 1
	s_lshl_b32 s4, s2, 2
	s_and_b32 s5, s5, 0xb00
	s_and_b32 s10, s10, 0xf80
	s_and_b32 s4, s4, 64
	s_add_i32 s5, s5, s10
	s_lshl_b32 s3, s3, 6
	s_or_b32 s4, s5, s4
	s_and_b32 s3, s3, 0x3c0
	s_lshl_b32 s4, s4, 2
	v_and_b32_e32 v0, 63, v14
	s_waitcnt lgkmcnt(0)
	s_add_u32 s4, s14, s4
	v_mov_b32_e32 v9, 0
	s_addc_u32 s5, s15, 0
	v_lshlrev_b32_e32 v8, 2, v0
	v_ashrrev_i32_e32 v15, 6, v14
	v_lshl_add_u64 v[10:11], s[4:5], 0, v[8:9]
	v_add_u32_e32 v2, s3, v15
	s_movk_i32 s4, 0x5800
	v_mad_i64_i32 v[0:1], s[10:11], v2, s4, v[10:11]
	s_mov_b32 s100, 0
	global_load_dword v0, v[0:1], off
	s_cmp_lg_u64 s[12:13], 0
	s_cselect_b64 s[16:17], -1, 0
	s_cmp_eq_u64 s[12:13], 0
	s_cbranch_scc1 .LBB0_1100
	v_ashrrev_i32_e32 v3, 31, v2
	v_lshl_add_u64 v[2:3], v[2:3], 2, s[12:13]
	global_load_dword v200, v[2:3], off
.LBB0_1100:
	v_add_u32_e32 v1, 0x200, v14
	v_ashrrev_i32_e32 v24, 6, v1
	v_add_u32_e32 v2, s3, v24
	v_mad_i64_i32 v[4:5], s[4:5], v2, s4, v[10:11]
	global_load_dword v1, v[4:5], off
	v_cndmask_b32_e64 v3, 0, 1, s[16:17]
	v_cmp_ne_u32_e64 s[4:5], 1, v3
	s_andn2_b64 vcc, exec, s[16:17]
	s_cbranch_vccnz .LBB0_1102
	v_ashrrev_i32_e32 v3, 31, v2
	v_lshl_add_u64 v[2:3], v[2:3], 2, s[12:13]
	global_load_dword v201, v[2:3], off
.LBB0_1102:
	v_add_u32_e32 v2, 0x400, v14
	v_ashrrev_i32_e32 v23, 6, v2
	v_add_u32_e32 v4, s3, v23
	s_movk_i32 s10, 0x5800
	v_mad_i64_i32 v[2:3], s[16:17], v4, s10, v[10:11]
	global_load_dword v2, v[2:3], off
	s_and_b64 vcc, exec, s[4:5]
	s_cbranch_vccnz .LBB0_1104
	v_ashrrev_i32_e32 v5, 31, v4
	v_lshl_add_u64 v[4:5], v[4:5], 2, s[12:13]
	global_load_dword v202, v[4:5], off
.LBB0_1104:
	v_add_u32_e32 v3, 0x600, v14
	v_ashrrev_i32_e32 v22, 6, v3
	v_add_u32_e32 v4, s3, v22
	v_mad_i64_i32 v[6:7], s[10:11], v4, s10, v[10:11]
	global_load_dword v3, v[6:7], off
	s_and_b64 vcc, exec, s[4:5]
	s_cbranch_vccnz .LBB0_1106
	v_ashrrev_i32_e32 v5, 31, v4
	v_lshl_add_u64 v[4:5], v[4:5], 2, s[12:13]
	global_load_dword v203, v[4:5], off
.LBB0_1106:
	v_add_u32_e32 v4, 0x800, v14
	v_ashrrev_i32_e32 v21, 6, v4
	v_add_u32_e32 v6, s3, v21
	s_movk_i32 s10, 0x5800
	v_mad_i64_i32 v[4:5], s[16:17], v6, s10, v[10:11]
	global_load_dword v4, v[4:5], off
	s_and_b64 vcc, exec, s[4:5]
	s_cbranch_vccnz .LBB0_1108
	v_ashrrev_i32_e32 v7, 31, v6
	v_lshl_add_u64 v[6:7], v[6:7], 2, s[12:13]
	global_load_dword v204, v[6:7], off
.LBB0_1108:
	v_add_u32_e32 v5, 0xa00, v14
	v_ashrrev_i32_e32 v20, 6, v5
	v_add_u32_e32 v6, s3, v20
	v_mad_i64_i32 v[12:13], s[10:11], v6, s10, v[10:11]
	global_load_dword v5, v[12:13], off
	s_and_b64 vcc, exec, s[4:5]
	s_cbranch_vccnz .LBB0_1110
	v_ashrrev_i32_e32 v7, 31, v6
	v_lshl_add_u64 v[6:7], v[6:7], 2, s[12:13]
	global_load_dword v205, v[6:7], off
.LBB0_1110:
	v_add_u32_e32 v6, 0xc00, v14
	v_ashrrev_i32_e32 v19, 6, v6
	v_add_u32_e32 v12, s3, v19
	s_movk_i32 s10, 0x5800
	v_mad_i64_i32 v[6:7], s[16:17], v12, s10, v[10:11]
	global_load_dword v6, v[6:7], off
	s_and_b64 vcc, exec, s[4:5]
	s_cbranch_vccnz .LBB0_1112
	v_ashrrev_i32_e32 v13, 31, v12
	v_lshl_add_u64 v[12:13], v[12:13], 2, s[12:13]
	global_load_dword v206, v[12:13], off
.LBB0_1112:
	v_add_u32_e32 v7, 0xe00, v14
	v_ashrrev_i32_e32 v18, 6, v7
	v_add_u32_e32 v12, s3, v18
	v_mad_i64_i32 v[10:11], s[10:11], v12, s10, v[10:11]
	global_load_dword v7, v[10:11], off
	s_and_b64 vcc, exec, s[4:5]
	s_cbranch_vccnz .LBB0_1114
	v_ashrrev_i32_e32 v13, 31, v12
	v_lshl_add_u64 v[10:11], v[12:13], 2, s[12:13]
	global_load_dword v207, v[10:11], off
	s_mov_b32 s100, 1

.LBB0_1116:
	s_add_i32 s19, s2, s3
	s_cmpk_gt_i32 s19, 0x57f
	s_cselect_b64 s[14:15], -1, 0
	s_and_b64 vcc, exec, s[14:15]
	s_waitcnt vmcnt(0)
	s_cmp_eq_u32 s100, 0
	s_cbranch_scc1 .Lp6nm_0
	v_mul_f32_e32 v0, v0, v200
	v_mul_f32_e32 v1, v1, v201
	v_mul_f32_e32 v2, v2, v202
	v_mul_f32_e32 v3, v3, v203
	v_mul_f32_e32 v4, v4, v204
	v_mul_f32_e32 v5, v5, v205
	v_mul_f32_e32 v6, v6, v206
	v_mul_f32_e32 v7, v7, v207
.Lp6nm_0:
	ds_write_b32 v26, v0
	s_waitcnt vmcnt(6)
	ds_write_b32 v27, v1
	s_waitcnt vmcnt(5)
	ds_write_b32 v28, v2
	s_waitcnt vmcnt(4)
	ds_write_b32 v29, v3
	s_waitcnt vmcnt(3)
	ds_write_b32 v30, v4
	s_waitcnt vmcnt(2)
	ds_write_b32 v31, v5
	s_waitcnt vmcnt(1)
	ds_write_b32 v32, v6
	s_waitcnt vmcnt(0)
	ds_write_b32 v33, v7
	s_waitcnt lgkmcnt(0)
	s_barrier
	s_cbranch_vccnz .LBB0_1115
	s_ashr_i32 s20, s19, 31
	s_lshr_b32 s20, s20, 28
	s_add_i32 s20, s19, s20
	s_ashr_i32 s22, s20, 4
	s_bfe_i32 s21, s22, 0x10001
	s_lshl_b32 s23, s22, 5
	s_lshl_b32 s20, s22, 6
	s_and_b32 s21, s21, 0xb00
	s_and_b32 s23, s23, 0xffffff80
	s_and_b32 s20, s20, 64
	s_add_i32 s21, s21, s23
	s_or_b32 s20, s21, s20
	s_ashr_i32 s21, s20, 31
	v_lshl_add_u64 v[12:13], s[20:21], 2, v[10:11]
	s_lshl_b32 s20, s22, 10
	s_sub_i32 s21, s10, s20
	v_add_u32_e32 v2, s21, v25
	v_mad_i64_i32 v[0:1], s[22:23], v2, s16, v[12:13]
	s_mov_b32 s100, 0
	global_load_dword v0, v[0:1], off
	s_and_b64 vcc, exec, s[4:5]
	s_cbranch_vccnz .LBB0_1119
	v_ashrrev_i32_e32 v3, 31, v2
	v_lshl_add_u64 v[2:3], v[2:3], 2, s[12:13]
	global_load_dword v200, v[2:3], off
.LBB0_1119:
	s_sub_i32 s20, 0, s20
	s_add_i32 s20, s20, s10
	v_add_u32_e32 v2, s20, v24
	v_mad_i64_i32 v[4:5], s[22:23], v2, s16, v[12:13]
	global_load_dword v1, v[4:5], off
	s_and_b64 vcc, exec, s[4:5]
	s_cbranch_vccnz .LBB0_1121
	v_ashrrev_i32_e32 v3, 31, v2
	v_lshl_add_u64 v[2:3], v[2:3], 2, s[12:13]
	global_load_dword v201, v[2:3], off
.LBB0_1121:
	v_add_u32_e32 v4, s20, v23
	v_mad_i64_i32 v[2:3], s[22:23], v4, s16, v[12:13]
	global_load_dword v2, v[2:3], off
	s_and_b64 vcc, exec, s[4:5]
	s_cbranch_vccnz .LBB0_1123
	v_ashrrev_i32_e32 v5, 31, v4
	v_lshl_add_u64 v[4:5], v[4:5], 2, s[12:13]
	global_load_dword v202, v[4:5], off
.LBB0_1123:
	v_add_u32_e32 v4, s20, v22
	v_mad_i64_i32 v[6:7], s[22:23], v4, s16, v[12:13]
	global_load_dword v3, v[6:7], off
	s_and_b64 vcc, exec, s[4:5]
	s_cbranch_vccnz .LBB0_1125
	v_ashrrev_i32_e32 v5, 31, v4
	v_lshl_add_u64 v[4:5], v[4:5], 2, s[12:13]
	global_load_dword v203, v[4:5], off
.LBB0_1125:
	v_add_u32_e32 v6, s20, v21
	v_mad_i64_i32 v[4:5], s[22:23], v6, s16, v[12:13]
	global_load_dword v4, v[4:5], off
	s_and_b64 vcc, exec, s[4:5]
	s_cbranch_vccnz .LBB0_1127
	v_ashrrev_i32_e32 v7, 31, v6
	v_lshl_add_u64 v[6:7], v[6:7], 2, s[12:13]
	global_load_dword v204, v[6:7], off
.LBB0_1127:
	v_add_u32_e32 v6, s20, v20
	v_mad_i64_i32 v[14:15], s[22:23], v6, s16, v[12:13]
	global_load_dword v5, v[14:15], off
	s_and_b64 vcc, exec, s[4:5]
	s_cbranch_vccnz .LBB0_1129
	v_ashrrev_i32_e32 v7, 31, v6
	v_lshl_add_u64 v[6:7], v[6:7], 2, s[12:13]
	global_load_dword v205, v[6:7], off
.LBB0_1129:
	v_add_u32_e32 v14, s20, v19
	v_mad_i64_i32 v[6:7], s[22:23], v14, s16, v[12:13]
	global_load_dword v6, v[6:7], off
	s_and_b64 vcc, exec, s[4:5]
	s_cbranch_vccnz .LBB0_1131
	v_ashrrev_i32_e32 v15, 31, v14
	v_lshl_add_u64 v[14:15], v[14:15], 2, s[12:13]
	global_load_dword v206, v[14:15], off
.LBB0_1131:
	v_add_u32_e32 v14, s20, v18
	v_mad_i64_i32 v[12:13], s[20:21], v14, s16, v[12:13]
	global_load_dword v7, v[12:13], off
	s_and_b64 vcc, exec, s[4:5]
	s_cbranch_vccnz .LBB0_1115
	v_ashrrev_i32_e32 v15, 31, v14
	v_lshl_add_u64 v[12:13], v[14:15], 2, s[12:13]
	global_load_dword v207, v[12:13], off
	s_mov_b32 s100, 1
	s_branch .LBB0_1115
